# v37 plus NA softmax reductions via v_permlane16_swap / v_permlane32_swap instead of ds_bpermute LDS round trips (bit-identical max / commutative add)
# speedup vs baseline: 1.0046x; 1.0046x over previous
; #define LAS __attribute__((address_space(3)))
; #define MFMA32(a, b, c) __builtin_amdgcn_mfma_f32_16x16x32_bf16((a), (b), (c), 0, 0, 0)
; DI void na_phase(LAS unsigned char* lds, const Args& A, const bf16* proj, bf16* nao, int T, int nB, unsigned* counter, int tid_in) {
;     ...
;             for (int rr = 0; rr < 4; ++rr) { const int kr = rs + 4 * kh + rr, sl = kr & 7;
; #pragma unroll
;                 for (int ct = 0; ct < 2; ++ct) { const int cm = cs0 + 16 * ct + l15; f32x4 acc = (f32x4){0.f, 0.f, 0.f, 0.f};
; #pragma unroll
;                     for (int ks = 0; ks < 2; ++ks) { const bf16x8 kf = *(const LAS bf16x8*)(lds + NA_K + sl * 8192 + cm * 128 + (((4 * ks + g) ^ ((cm >> 1) & 7)) * 16)); acc = MFMA32(kf, qf[ks], acc); }
; #pragma unroll
;                     for (int e = 0; e < 4; ++e) { const int cc = cs0 + 16 * ct + 4 * g + e; const bool valid = (cc >= csq) && (cc < csq + 16);
;                         const int bi = (kr - r + 7) * 31 + min(max(cc - cq + 15, 0), 30);
;                         const float sv = valid ? acc[e] + BI[bi] : -INFINITY; acc[e] = sv; mx = fmaxf(mx, sv); }
;                     sT[rr][ct] = acc; } }
.LBB0_337:
	v_add_u32_e32 v31, s38, v71
	v_lshlrev_b32_e32 v24, 13, v31
	v_and_b32_e32 v28, 0xe000, v24
	v_add_u32_e32 v30, 0, v28
	v_add_u32_e32 v29, v30, v91
	v_add_u32_e32 v24, v29, v92
	ds_read_b128 v[24:27], v24
	v_add_u32_e32 v29, v29, v93
	ds_read_b128 v[58:61], v29
	s_add_i32 s0, s19, s38
	v_add_u32_e32 v29, s0, v57
	v_mul_lo_u32 v29, v29, s88
	v_add_u32_e32 v38, s87, v29
	v_add_u32_e32 v29, 0xfffff080, v38
	v_mov_b32_e32 v63, 0xff800000
	v_lshl_add_u32 v252, v94, 2, v29
	ds_read_b32 v252, v252 offset:868
	v_lshl_add_u32 v253, v95, 2, v29
	ds_read_b32 v253, v253 offset:868
	v_lshl_add_u32 v254, v96, 2, v29
	ds_read_b32 v254, v254 offset:868
	v_lshl_add_u32 v255, v97, 2, v29
	ds_read_b32 v255, v255 offset:868
	s_waitcnt lgkmcnt(5)
	v_mfma_f32_16x16x32_bf16 v[24:27], v[24:27], v[20:23], 0
	s_waitcnt lgkmcnt(4)
	v_mfma_f32_16x16x32_bf16 v[24:27], v[58:61], v[16:19], v[24:27]
	v_mov_b32_e32 v59, 0xff800000
	s_waitcnt lgkmcnt(0)
	s_nop 5
	s_and_saveexec_b64 s[0:1], s[14:15]
	v_add_f32_e32 v63, v24, v252
	s_or_b64 exec, exec, s[0:1]
	s_and_saveexec_b64 s[0:1], s[16:17]
	v_add_f32_e32 v59, v25, v253
	s_or_b64 exec, exec, s[0:1]
	v_mov_b32_e32 v56, 0xff800000
	v_mov_b32_e32 v62, 0xff800000
	s_and_saveexec_b64 s[0:1], s[48:49]
	v_add_f32_e32 v62, v26, v254
	s_or_b64 exec, exec, s[0:1]
	s_and_saveexec_b64 s[0:1], s[50:51]
	v_add_f32_e32 v56, v27, v255
	s_or_b64 exec, exec, s[0:1]
	v_add_u32_e32 v30, v30, v98
	v_add_u32_e32 v24, v30, v92
	ds_read_b128 v[24:27], v24
	v_add_u32_e32 v30, v30, v93
	ds_read_b128 v[64:67], v30
	v_mov_b32_e32 v39, 0xff800000
	v_lshl_add_u32 v252, v99, 2, v29
	ds_read_b32 v252, v252 offset:868
	v_lshl_add_u32 v253, v100, 2, v29
	ds_read_b32 v253, v253 offset:868
	v_lshl_add_u32 v254, v101, 2, v29
	ds_read_b32 v254, v254 offset:868
	v_lshl_add_u32 v255, v102, 2, v29
	ds_read_b32 v255, v255 offset:868
	s_waitcnt lgkmcnt(5)
	v_mfma_f32_16x16x32_bf16 v[24:27], v[24:27], v[20:23], 0
	s_waitcnt lgkmcnt(4)
	v_mfma_f32_16x16x32_bf16 v[24:27], v[64:67], v[16:19], v[24:27]
	v_mov_b32_e32 v65, 0xff800000
	s_waitcnt lgkmcnt(0)
	s_nop 5
	s_and_saveexec_b64 s[0:1], s[52:53]
	v_add_f32_e32 v65, v24, v252
	s_or_b64 exec, exec, s[0:1]
	s_and_saveexec_b64 s[0:1], s[56:57]
	v_add_f32_e32 v39, v25, v253
	s_or_b64 exec, exec, s[0:1]
	v_mov_b32_e32 v54, 0xff800000
	v_mov_b32_e32 v55, 0xff800000
	s_and_saveexec_b64 s[0:1], s[76:77]
	v_add_f32_e32 v55, v26, v254
	s_or_b64 exec, exec, s[0:1]
	s_and_saveexec_b64 s[0:1], s[66:67]
	v_add_f32_e32 v54, v27, v255
	s_or_b64 exec, exec, s[0:1]
	v_lshl_add_u32 v24, v31, 13, v212
	v_and_b32_e32 v29, 0xe000, v24
	v_add_u32_e32 v66, 0, v29
	v_add_u32_e32 v30, v66, v91
	v_add_u32_e32 v24, v30, v92
	ds_read_b128 v[24:27], v24
	v_add_u32_e32 v30, v30, v93
	ds_read_b128 v[104:107], v30
	v_add_u32_e32 v30, 0xfffff0fc, v38
	v_mov_b32_e32 v58, 0xff800000
	v_mov_b32_e32 v60, 0xff800000
	v_lshl_add_u32 v252, v94, 2, v30
	ds_read_b32 v252, v252 offset:868
	v_lshl_add_u32 v253, v95, 2, v30
	ds_read_b32 v253, v253 offset:868
	v_lshl_add_u32 v254, v96, 2, v30
	ds_read_b32 v254, v254 offset:868
	v_lshl_add_u32 v255, v97, 2, v30
	ds_read_b32 v255, v255 offset:868
	s_waitcnt lgkmcnt(5)
	v_mfma_f32_16x16x32_bf16 v[24:27], v[24:27], v[20:23], 0
	s_waitcnt lgkmcnt(4)
	v_mfma_f32_16x16x32_bf16 v[24:27], v[104:107], v[16:19], v[24:27]
	s_waitcnt lgkmcnt(0)
	s_nop 5
	s_and_saveexec_b64 s[0:1], s[14:15]
	v_add_f32_e32 v60, v24, v252
	s_or_b64 exec, exec, s[0:1]
	s_and_saveexec_b64 s[0:1], s[16:17]
	v_add_f32_e32 v58, v25, v253
	s_or_b64 exec, exec, s[0:1]
	v_mov_b32_e32 v61, 0xff800000
	v_mov_b32_e32 v64, 0xff800000
	s_and_saveexec_b64 s[0:1], s[48:49]
	v_add_f32_e32 v64, v26, v254
	s_or_b64 exec, exec, s[0:1]
	s_and_saveexec_b64 s[0:1], s[50:51]
	v_add_f32_e32 v61, v27, v255
	s_or_b64 exec, exec, s[0:1]
	v_add_u32_e32 v66, v66, v98
	v_add_u32_e32 v24, v66, v92
	ds_read_b128 v[24:27], v24
	v_add_u32_e32 v66, v66, v93
	ds_read_b128 v[104:107], v66
	v_mov_b32_e32 v66, 0xff800000
	v_mov_b32_e32 v67, 0xff800000
	v_lshl_add_u32 v252, v99, 2, v30
	ds_read_b32 v252, v252 offset:868
	v_lshl_add_u32 v253, v100, 2, v30
	ds_read_b32 v253, v253 offset:868
	v_lshl_add_u32 v254, v101, 2, v30
	ds_read_b32 v254, v254 offset:868
	v_lshl_add_u32 v255, v102, 2, v30
	ds_read_b32 v255, v255 offset:868
	s_waitcnt lgkmcnt(5)
	v_mfma_f32_16x16x32_bf16 v[24:27], v[24:27], v[20:23], 0
	s_waitcnt lgkmcnt(4)
	v_mfma_f32_16x16x32_bf16 v[24:27], v[104:107], v[16:19], v[24:27]
	s_waitcnt lgkmcnt(0)
	s_nop 5
	s_and_saveexec_b64 s[0:1], s[52:53]
	v_add_f32_e32 v67, v24, v252
	s_or_b64 exec, exec, s[0:1]
	s_and_saveexec_b64 s[0:1], s[56:57]
	v_add_f32_e32 v66, v25, v253
	s_or_b64 exec, exec, s[0:1]
	v_mov_b32_e32 v104, 0xff800000
	v_mov_b32_e32 v105, 0xff800000
	s_and_saveexec_b64 s[0:1], s[76:77]
	v_add_f32_e32 v105, v26, v254
	s_or_b64 exec, exec, s[0:1]
	s_and_saveexec_b64 s[0:1], s[66:67]
	v_add_f32_e32 v104, v27, v255
	s_or_b64 exec, exec, s[0:1]
	v_lshl_add_u32 v24, v31, 13, v213
	v_and_b32_e32 v30, 0xe000, v24
	v_add_u32_e32 v110, 0, v30
	v_add_u32_e32 v106, v110, v91
	v_add_u32_e32 v24, v106, v92
	ds_read_b128 v[24:27], v24
	v_add_u32_e32 v106, v106, v93
	ds_read_b128 v[106:109], v106
	v_add_u32_e32 v114, 0xfffff178, v38
	v_lshl_add_u32 v252, v94, 2, v114
	ds_read_b32 v252, v252 offset:868
	v_lshl_add_u32 v253, v95, 2, v114
	ds_read_b32 v253, v253 offset:868
	v_lshl_add_u32 v254, v96, 2, v114
	ds_read_b32 v254, v254 offset:868
	v_lshl_add_u32 v255, v97, 2, v114
	ds_read_b32 v255, v255 offset:868
	s_waitcnt lgkmcnt(5)
	v_mfma_f32_16x16x32_bf16 v[24:27], v[24:27], v[20:23], 0
	s_waitcnt lgkmcnt(4)
; #define LAS __attribute__((address_space(3)))
; #define MFMA32(a, b, c) __builtin_amdgcn_mfma_f32_16x16x32_bf16((a), (b), (c), 0, 0, 0)
; DI void na_phase(LAS unsigned char* lds, const Args& A, const bf16* proj, bf16* nao, int T, int nB, unsigned* counter, int tid_in) {
;     ...
;             for (int rr = 0; rr < 4; ++rr) { const int kr = rs + 4 * kh + rr, sl = kr & 7;
; #pragma unroll
;                 for (int ct = 0; ct < 2; ++ct) { const int cm = cs0 + 16 * ct + l15; f32x4 acc = (f32x4){0.f, 0.f, 0.f, 0.f};
; #pragma unroll
;                     for (int ks = 0; ks < 2; ++ks) { const bf16x8 kf = *(const LAS bf16x8*)(lds + NA_K + sl * 8192 + cm * 128 + (((4 * ks + g) ^ ((cm >> 1) & 7)) * 16)); acc = MFMA32(kf, qf[ks], acc); }
; #pragma unroll
;                     for (int e = 0; e < 4; ++e) { const int cc = cs0 + 16 * ct + 4 * g + e; const bool valid = (cc >= csq) && (cc < csq + 16);
;                         const int bi = (kr - r + 7) * 31 + min(max(cc - cq + 15, 0), 30);
;                         const float sv = valid ? acc[e] + BI[bi] : -INFINITY; acc[e] = sv; mx = fmaxf(mx, sv); }
;                     sT[rr][ct] = acc; } }
;             mx = fmaxf(mx, __shfl_xor(mx, 16)); mx = fmaxf(mx, __shfl_xor(mx, 32));
;             float lsum = 0.f;
; #pragma unroll
;             for (int rr = 0; rr < 4; ++rr)
; #pragma unroll
;                 for (int ct = 0; ct < 2; ++ct)
; #pragma unroll
;                     for (int e = 0; e < 4; ++e) { const float p = __expf(sT[rr][ct][e] - mx); sT[rr][ct][e] = p; lsum += p; }
	v_mfma_f32_16x16x32_bf16 v[24:27], v[106:109], v[16:19], v[24:27]
	v_mov_b32_e32 v106, 0xff800000
	v_mov_b32_e32 v107, 0xff800000
	s_waitcnt lgkmcnt(0)
	s_nop 5
	s_and_saveexec_b64 s[0:1], s[14:15]
	v_add_f32_e32 v107, v24, v252
	s_or_b64 exec, exec, s[0:1]
	s_and_saveexec_b64 s[0:1], s[16:17]
	v_add_f32_e32 v106, v25, v253
	s_or_b64 exec, exec, s[0:1]
	v_mov_b32_e32 v108, 0xff800000
	v_mov_b32_e32 v109, 0xff800000
	s_and_saveexec_b64 s[0:1], s[48:49]
	v_add_f32_e32 v109, v26, v254
	s_or_b64 exec, exec, s[0:1]
	s_and_saveexec_b64 s[0:1], s[50:51]
	v_add_f32_e32 v108, v27, v255
	s_or_b64 exec, exec, s[0:1]
	v_add_u32_e32 v110, v110, v98
	v_add_u32_e32 v24, v110, v92
	ds_read_b128 v[24:27], v24
	v_add_u32_e32 v110, v110, v93
	ds_read_b128 v[110:113], v110
	v_lshl_add_u32 v252, v99, 2, v114
	ds_read_b32 v252, v252 offset:868
	v_lshl_add_u32 v253, v100, 2, v114
	ds_read_b32 v253, v253 offset:868
	v_lshl_add_u32 v254, v101, 2, v114
	ds_read_b32 v254, v254 offset:868
	v_lshl_add_u32 v255, v102, 2, v114
	ds_read_b32 v255, v255 offset:868
	s_waitcnt lgkmcnt(5)
	v_mfma_f32_16x16x32_bf16 v[24:27], v[24:27], v[20:23], 0
	s_waitcnt lgkmcnt(4)
	v_mfma_f32_16x16x32_bf16 v[24:27], v[110:113], v[16:19], v[24:27]
	v_mov_b32_e32 v110, 0xff800000
	v_mov_b32_e32 v111, 0xff800000
	s_waitcnt lgkmcnt(0)
	s_nop 5
	s_and_saveexec_b64 s[0:1], s[52:53]
	v_add_f32_e32 v111, v24, v252
	s_or_b64 exec, exec, s[0:1]
	s_and_saveexec_b64 s[0:1], s[56:57]
	v_add_f32_e32 v110, v25, v253
	s_or_b64 exec, exec, s[0:1]
	v_mov_b32_e32 v112, 0xff800000
	v_mov_b32_e32 v113, 0xff800000
	s_and_saveexec_b64 s[0:1], s[76:77]
	v_add_f32_e32 v113, v26, v254
	s_or_b64 exec, exec, s[0:1]
	s_and_saveexec_b64 s[0:1], s[66:67]
	v_add_f32_e32 v112, v27, v255
	s_or_b64 exec, exec, s[0:1]
	v_lshl_add_u32 v24, v31, 13, v214
	v_and_b32_e32 v31, 0xe000, v24
	v_add_u32_e32 v116, 0, v31
	v_add_u32_e32 v114, v116, v91
	v_add_u32_e32 v24, v114, v92
	ds_read_b128 v[24:27], v24
	v_add_u32_e32 v114, v114, v93
	ds_read_b128 v[118:121], v114
	v_add_u32_e32 v38, 0xfffff1f4, v38
	v_mov_b32_e32 v114, 0xff800000
	v_mov_b32_e32 v115, 0xff800000
	v_lshl_add_u32 v252, v94, 2, v38
	ds_read_b32 v252, v252 offset:868
	v_lshl_add_u32 v253, v95, 2, v38
	ds_read_b32 v253, v253 offset:868
	s_waitcnt lgkmcnt(3)
	v_mfma_f32_16x16x32_bf16 v[24:27], v[24:27], v[20:23], 0
	s_waitcnt lgkmcnt(2)
	v_mfma_f32_16x16x32_bf16 v[24:27], v[118:121], v[16:19], v[24:27]
	s_waitcnt lgkmcnt(0)
	s_nop 5
	s_and_saveexec_b64 s[0:1], s[14:15]
	v_add_f32_e32 v115, v24, v252
	s_or_b64 exec, exec, s[0:1]
	s_and_saveexec_b64 s[0:1], s[16:17]
	v_add_f32_e32 v114, v25, v253
	s_or_b64 exec, exec, s[0:1]
	s_nop 1
	v_mov_b32_e32 v24, 0xff800000
	v_mov_b32_e32 v25, 0xff800000
	v_lshl_add_u32 v252, v96, 2, v38
	ds_read_b32 v252, v252 offset:868
	v_lshl_add_u32 v253, v97, 2, v38
	ds_read_b32 v253, v253 offset:868
	s_waitcnt lgkmcnt(0)
	s_nop 2
	s_and_saveexec_b64 s[0:1], s[48:49]
	v_add_f32_e32 v25, v26, v252
	s_or_b64 exec, exec, s[0:1]
	s_and_saveexec_b64 s[0:1], s[50:51]
	v_add_f32_e32 v24, v27, v253
	s_or_b64 exec, exec, s[0:1]
	v_add_u32_e32 v26, v116, v98
	v_add_u32_e32 v27, v26, v92
	ds_read_b128 v[116:119], v27
	v_add_u32_e32 v26, v26, v93
	s_waitcnt lgkmcnt(0)
	v_mfma_f32_16x16x32_bf16 v[20:23], v[116:119], v[20:23], 0
	ds_read_b128 v[116:119], v26
	s_waitcnt lgkmcnt(0)
	v_mfma_f32_16x16x32_bf16 v[16:19], v[116:119], v[16:19], v[20:23]
	s_nop 4
	v_mov_b32_e32 v20, 0xff800000
	v_mov_b32_e32 v21, 0xff800000
	v_lshl_add_u32 v252, v99, 2, v38
	ds_read_b32 v252, v252 offset:868
	v_lshl_add_u32 v253, v100, 2, v38
	ds_read_b32 v253, v253 offset:868
	v_lshl_add_u32 v254, v101, 2, v38
	ds_read_b32 v254, v254 offset:868
	v_lshl_add_u32 v255, v102, 2, v38
	ds_read_b32 v255, v255 offset:868
	s_waitcnt lgkmcnt(0)
	s_and_saveexec_b64 s[0:1], s[52:53]
	v_add_f32_e32 v21, v16, v252
	s_or_b64 exec, exec, s[0:1]
	s_and_saveexec_b64 s[0:1], s[56:57]
	v_add_f32_e32 v20, v17, v253
	s_or_b64 exec, exec, s[0:1]
	v_mov_b32_e32 v16, 0xff800000
	v_mov_b32_e32 v17, 0xff800000
	s_and_saveexec_b64 s[0:1], s[76:77]
	v_add_f32_e32 v17, v18, v254
	s_or_b64 exec, exec, s[0:1]
	s_and_saveexec_b64 s[0:1], s[66:67]
	v_add_f32_e32 v16, v19, v255
	s_or_b64 exec, exec, s[0:1]
	v_max3_f32 v18, v63, s89, v59
	v_max3_f32 v18, v18, v62, v56
	v_max3_f32 v18, v18, v65, v39
	v_max3_f32 v18, v18, v55, v54
	v_max3_f32 v18, v18, v60, v58
	v_max3_f32 v18, v18, v64, v61
	v_max3_f32 v18, v18, v67, v66
	v_max3_f32 v18, v18, v105, v104
	v_max3_f32 v18, v18, v107, v106
	v_max3_f32 v18, v18, v109, v108
	v_max3_f32 v18, v18, v111, v110
	v_max3_f32 v18, v18, v113, v112
	v_max3_f32 v18, v18, v115, v114
	v_max3_f32 v18, v18, v25, v24
	v_max3_f32 v18, v18, v21, v20
	v_max3_f32 v18, v18, v17, v16
	v_mov_b32_e32 v19, v18
	s_nop 1
	v_permlane16_swap_b32_e32 v19, v18
	v_max_f32_e32 v18, v18, v19
	v_mov_b32_e32 v19, v18
	s_nop 1
	v_permlane32_swap_b32_e32 v19, v18
	v_max_f32_e32 v38, v18, v19
	v_sub_f32_e32 v39, v39, v38
	v_mul_f32_e32 v39, 0x3fb8aa3b, v39
	v_sub_f32_e32 v26, v56, v38
	v_exp_f32_e32 v56, v39
	v_sub_f32_e32 v39, v55, v38
	v_mul_f32_e32 v39, 0x3fb8aa3b, v39
	v_exp_f32_e32 v55, v39
	v_sub_f32_e32 v39, v54, v38
	v_mul_f32_e32 v39, 0x3fb8aa3b, v39
	v_sub_f32_e32 v22, v59, v38
	v_exp_f32_e32 v59, v39
	v_sub_f32_e32 v39, v60, v38
	v_mul_f32_e32 v39, 0x3fb8aa3b, v39
	v_exp_f32_e32 v116, v39
	v_sub_f32_e32 v39, v58, v38
	v_mul_f32_e32 v39, 0x3fb8aa3b, v39
	v_exp_f32_e32 v117, v39
	v_sub_f32_e32 v39, v64, v38
	v_mul_f32_e32 v39, 0x3fb8aa3b, v39
	v_exp_f32_e32 v118, v39
	v_sub_f32_e32 v39, v61, v38
	v_mul_f32_e32 v39, 0x3fb8aa3b, v39
	v_exp_f32_e32 v119, v39
	v_sub_f32_e32 v39, v67, v38
; #define LAS __attribute__((address_space(3)))
; DI unsigned pk2(float lo, float hi) { f32x2 v = {lo, hi}; bf16v2 b = __builtin_convertvector(v, bf16v2); return __builtin_bit_cast(unsigned, b); }
; #define MFMA32(a, b, c) __builtin_amdgcn_mfma_f32_16x16x32_bf16((a), (b), (c), 0, 0, 0)
; DI void na_phase(LAS unsigned char* lds, const Args& A, const bf16* proj, bf16* nao, int T, int nB, unsigned* counter, int tid_in) {
;     ...
;             float lsum = 0.f;
; #pragma unroll
;             for (int rr = 0; rr < 4; ++rr)
; #pragma unroll
;                 for (int ct = 0; ct < 2; ++ct)
; #pragma unroll
;                     for (int e = 0; e < 4; ++e) { const float p = __expf(sT[rr][ct][e] - mx); sT[rr][ct][e] = p; lsum += p; }
;             lsum += __shfl_xor(lsum, 16); lsum += __shfl_xor(lsum, 32);
;             f32x4 O[4];
; #pragma unroll
;             for (int mt = 0; mt < 4; ++mt) O[mt] = (f32x4){0.f, 0.f, 0.f, 0.f};
; #pragma unroll
;             for (int rr = 0; rr < 4; ++rr) { const int sl = (rs + 4 * kh + rr) & 7;
;                 const u32x4 pw = (u32x4){pk2(sT[rr][0][0], sT[rr][0][1]), pk2(sT[rr][0][2], sT[rr][0][3]), pk2(sT[rr][1][0], sT[rr][1][1]), pk2(sT[rr][1][2], sT[rr][1][3])};
;                 const bf16x8 pb = __builtin_bit_cast(bf16x8, pw);
; #pragma unroll
;                 for (int mt = 0; mt < 4; ++mt) { const int dd = 16 * mt + l15, sw = 2 * ((dd >> 1) & 7);
;                     const LAS unsigned char* vb = lds + NA_V + sl * 8192 + dd * 128;
;                     const u32x2 lo = *(const LAS u32x2*)(vb + ((((cs0 >> 2) + g) ^ sw) * 8)), hi = *(const LAS u32x2*)(vb + ((((cs0 >> 2) + 4 + g) ^ sw) * 8));
;                     const u32x4 vv = (u32x4){lo.x, lo.y, hi.x, hi.y};
;                     O[mt] = MFMA32(__builtin_bit_cast(bf16x8, vv), pb, O[mt]); } }
	v_sub_f32_e32 v18, v63, v38
	v_mul_f32_e32 v39, 0x3fb8aa3b, v39
	v_mul_f32_e32 v18, 0x3fb8aa3b, v18
	v_exp_f32_e32 v67, v39
	v_sub_f32_e32 v39, v66, v38
	v_exp_f32_e32 v18, v18
	v_mul_f32_e32 v22, 0x3fb8aa3b, v22
	v_sub_f32_e32 v23, v62, v38
	v_mul_f32_e32 v39, 0x3fb8aa3b, v39
	v_exp_f32_e32 v22, v22
	v_mul_f32_e32 v23, 0x3fb8aa3b, v23
	v_exp_f32_e32 v66, v39
	v_sub_f32_e32 v39, v105, v38
	v_exp_f32_e32 v23, v23
	v_mul_f32_e32 v26, 0x3fb8aa3b, v26
	v_sub_f32_e32 v27, v65, v38
	v_mul_f32_e32 v39, 0x3fb8aa3b, v39
	v_exp_f32_e32 v26, v26
	v_mul_f32_e32 v27, 0x3fb8aa3b, v27
	v_exp_f32_e32 v120, v39
	v_sub_f32_e32 v39, v104, v38
	v_add_f32_e32 v19, 0, v18
	v_exp_f32_e32 v27, v27
	v_mul_f32_e32 v39, 0x3fb8aa3b, v39
	v_add_f32_e32 v19, v22, v19
	v_exp_f32_e32 v121, v39
	v_sub_f32_e32 v39, v107, v38
	v_add_f32_e32 v19, v23, v19
	v_mul_f32_e32 v39, 0x3fb8aa3b, v39
	v_add_f32_e32 v19, v26, v19
	v_exp_f32_e32 v122, v39
	v_sub_f32_e32 v39, v106, v38
	v_add_f32_e32 v19, v27, v19
	v_mul_f32_e32 v39, 0x3fb8aa3b, v39
	v_add_f32_e32 v19, v56, v19
	v_exp_f32_e32 v123, v39
	v_sub_f32_e32 v39, v109, v38
	v_add_f32_e32 v19, v55, v19
	v_mul_f32_e32 v39, 0x3fb8aa3b, v39
	v_add_f32_e32 v19, v59, v19
	v_exp_f32_e32 v124, v39
	v_sub_f32_e32 v39, v108, v38
	v_add_f32_e32 v19, v116, v19
	v_mul_f32_e32 v39, 0x3fb8aa3b, v39
	v_add_f32_e32 v19, v117, v19
	v_exp_f32_e32 v125, v39
	v_sub_f32_e32 v39, v111, v38
	v_add_f32_e32 v19, v118, v19
	v_mul_f32_e32 v39, 0x3fb8aa3b, v39
	v_add_f32_e32 v19, v119, v19
	v_exp_f32_e32 v126, v39
	v_sub_f32_e32 v39, v110, v38
	v_add_f32_e32 v19, v67, v19
	v_mul_f32_e32 v39, 0x3fb8aa3b, v39
	v_add_f32_e32 v19, v66, v19
	v_exp_f32_e32 v127, v39
	v_sub_f32_e32 v39, v113, v38
	v_add_f32_e32 v19, v120, v19
	v_mul_f32_e32 v39, 0x3fb8aa3b, v39
	v_add_f32_e32 v19, v121, v19
	v_exp_f32_e32 v128, v39
	v_sub_f32_e32 v39, v112, v38
	v_add_f32_e32 v19, v122, v19
	v_mul_f32_e32 v39, 0x3fb8aa3b, v39
	v_add_f32_e32 v19, v123, v19
	v_exp_f32_e32 v129, v39
	v_sub_f32_e32 v39, v115, v38
	v_add_f32_e32 v19, v124, v19
	v_mul_f32_e32 v39, 0x3fb8aa3b, v39
	v_add_f32_e32 v19, v125, v19
	v_exp_f32_e32 v130, v39
	v_sub_f32_e32 v39, v114, v38
	v_add_f32_e32 v19, v126, v19
	v_mul_f32_e32 v39, 0x3fb8aa3b, v39
	v_sub_f32_e32 v25, v25, v38
	v_add_f32_e32 v19, v127, v19
	v_exp_f32_e32 v131, v39
	v_mul_f32_e32 v25, 0x3fb8aa3b, v25
	v_sub_f32_e32 v24, v24, v38
	v_add_f32_e32 v19, v128, v19
	v_exp_f32_e32 v132, v25
	v_mul_f32_e32 v24, 0x3fb8aa3b, v24
	v_sub_f32_e32 v21, v21, v38
	v_add_f32_e32 v19, v129, v19
	v_exp_f32_e32 v133, v24
	v_mul_f32_e32 v21, 0x3fb8aa3b, v21
	v_sub_f32_e32 v20, v20, v38
	v_add_f32_e32 v19, v130, v19
	v_exp_f32_e32 v134, v21
	v_mul_f32_e32 v20, 0x3fb8aa3b, v20
	v_sub_f32_e32 v17, v17, v38
	v_add_f32_e32 v19, v131, v19
	v_exp_f32_e32 v135, v20
	v_mul_f32_e32 v17, 0x3fb8aa3b, v17
	v_sub_f32_e32 v16, v16, v38
	v_add_f32_e32 v19, v132, v19
	v_exp_f32_e32 v136, v17
	v_mul_f32_e32 v16, 0x3fb8aa3b, v16
	v_add_f32_e32 v19, v133, v19
	v_exp_f32_e32 v137, v16
	v_add_f32_e32 v19, v134, v19
	v_add_f32_e32 v19, v135, v19
	v_add_f32_e32 v17, v136, v19
	v_add_f32_e32 v16, v137, v17
	v_mov_b32_e32 v17, v16
	s_nop 1
	v_permlane16_swap_b32_e32 v17, v16
	v_add_u32_e32 v24, v74, v28
	v_cvt_pk_bf16_f32 v19, v55, v59
	v_add_u32_e32 v28, v24, v75
	v_add_u32_e32 v55, v24, v76
	s_waitcnt lgkmcnt(0)
	v_add_f32_e32 v39, v16, v17
	v_cvt_pk_bf16_f32 v16, v18, v22
	v_cvt_pk_bf16_f32 v17, v23, v26
	v_cvt_pk_bf16_f32 v18, v27, v56
	ds_read2st64_b64 v[20:23], v28 offset1:4
	ds_read2st64_b64 v[24:27], v55 offset1:4
	v_mov_b32_e32 v54, v39
	s_nop 1
	v_permlane32_swap_b32_e32 v54, v39
	s_waitcnt lgkmcnt(1)
	v_mov_b32_e32 v58, v20
	s_waitcnt lgkmcnt(0)
	v_mov_b32_e32 v60, v24
	v_mov_b32_e32 v61, v25
	v_mov_b32_e32 v24, v22
	v_mov_b32_e32 v25, v23
	v_mov_b32_e32 v59, v21
	v_add_f32_e32 v54, v39, v54
	v_mfma_f32_16x16x32_bf16 v[20:23], v[24:27], v[16:19], 0
	ds_read2st64_b64 v[24:27], v28 offset0:8 offset1:12
	ds_read2st64_b64 v[62:65], v55 offset0:8 offset1:12
	v_add_u32_e32 v28, v74, v29
	v_add_u32_e32 v29, v28, v75
	v_add_u32_e32 v28, v28, v76
	s_waitcnt lgkmcnt(1)
; #define LAS __attribute__((address_space(3)))
; DI unsigned pk2(float lo, float hi) { f32x2 v = {lo, hi}; bf16v2 b = __builtin_convertvector(v, bf16v2); return __builtin_bit_cast(unsigned, b); }
; #define MFMA32(a, b, c) __builtin_amdgcn_mfma_f32_16x16x32_bf16((a), (b), (c), 0, 0, 0)
; DI void na_phase(LAS unsigned char* lds, const Args& A, const bf16* proj, bf16* nao, int T, int nB, unsigned* counter, int tid_in) {
;     ...
; #pragma unroll
;             for (int rr = 0; rr < 4; ++rr) { const int sl = (rs + 4 * kh + rr) & 7;
;                 const u32x4 pw = (u32x4){pk2(sT[rr][0][0], sT[rr][0][1]), pk2(sT[rr][0][2], sT[rr][0][3]), pk2(sT[rr][1][0], sT[rr][1][1]), pk2(sT[rr][1][2], sT[rr][1][3])};
;                 const bf16x8 pb = __builtin_bit_cast(bf16x8, pw);
; #pragma unroll
;                 for (int mt = 0; mt < 4; ++mt) { const int dd = 16 * mt + l15, sw = 2 * ((dd >> 1) & 7);
;                     const LAS unsigned char* vb = lds + NA_V + sl * 8192 + dd * 128;
;                     const u32x2 lo = *(const LAS u32x2*)(vb + ((((cs0 >> 2) + g) ^ sw) * 8)), hi = *(const LAS u32x2*)(vb + ((((cs0 >> 2) + 4 + g) ^ sw) * 8));
;                     const u32x4 vv = (u32x4){lo.x, lo.y, hi.x, hi.y};
;                     O[mt] = MFMA32(__builtin_bit_cast(bf16x8, vv), pb, O[mt]); } }
;             LAS float* MG = (LAS float*)(lds + NA_MRG + qg * 4608) + lane;
;             if (kh == 1) { MG[0] = mx; MG[64] = lsum;
; #pragma unroll
;                 for (int mt = 0; mt < 4; ++mt)
; #pragma unroll
;                     for (int e = 0; e < 4; ++e) MG[(2 + mt * 4 + e) * 64] = O[mt][e]; }
	v_mov_b32_e32 v104, v24
	v_mov_b32_e32 v105, v25
	s_waitcnt lgkmcnt(0)
	v_mov_b32_e32 v106, v62
	v_mov_b32_e32 v107, v63
	v_mov_b32_e32 v62, v26
	v_mov_b32_e32 v63, v27
	v_mfma_f32_16x16x32_bf16 v[58:61], v[58:61], v[16:19], 0
	ds_read2st64_b64 v[108:111], v28 offset1:4
	v_cvt_pk_bf16_f32 v24, v116, v117
	v_cvt_pk_bf16_f32 v25, v118, v119
	v_mfma_f32_16x16x32_bf16 v[104:107], v[104:107], v[16:19], 0
	v_cvt_pk_bf16_f32 v26, v67, v66
	s_waitcnt lgkmcnt(0)
	v_mov_b32_e32 v114, v108
	v_mov_b32_e32 v115, v109
	v_mfma_f32_16x16x32_bf16 v[16:19], v[62:65], v[16:19], 0
	ds_read2st64_b64 v[62:65], v29 offset1:4
	v_cvt_pk_bf16_f32 v27, v120, v121
	s_waitcnt lgkmcnt(0)
	v_mov_b32_e32 v108, v64
	v_mov_b32_e32 v109, v65
	v_mov_b32_e32 v112, v62
	v_mov_b32_e32 v113, v63
	v_mfma_f32_16x16x32_bf16 v[20:23], v[108:111], v[24:27], v[20:23]
	ds_read2st64_b64 v[62:65], v29 offset0:8 offset1:12
	ds_read2st64_b64 v[108:111], v28 offset0:8 offset1:12
	v_add_u32_e32 v28, v74, v30
	v_add_u32_e32 v29, v28, v75
	v_mfma_f32_16x16x32_bf16 v[58:61], v[112:115], v[24:27], v[58:61]
	v_add_u32_e32 v28, v28, v76
	s_waitcnt lgkmcnt(0)
	v_mov_b32_e32 v114, v108
	v_mov_b32_e32 v115, v109
	v_mov_b32_e32 v108, v64
	v_mov_b32_e32 v109, v65
	v_mov_b32_e32 v112, v62
	v_mov_b32_e32 v113, v63
	v_mfma_f32_16x16x32_bf16 v[16:19], v[108:111], v[24:27], v[16:19]
	ds_read2st64_b64 v[62:65], v29 offset1:4
	ds_read2st64_b64 v[108:111], v28 offset1:4
	v_mfma_f32_16x16x32_bf16 v[104:107], v[112:115], v[24:27], v[104:107]
	v_cvt_pk_bf16_f32 v24, v122, v123
	v_cvt_pk_bf16_f32 v25, v124, v125
	s_waitcnt lgkmcnt(0)
	v_mov_b32_e32 v114, v108
	v_mov_b32_e32 v115, v109
	v_mov_b32_e32 v108, v64
	v_mov_b32_e32 v109, v65
	v_cvt_pk_bf16_f32 v26, v126, v127
	v_cvt_pk_bf16_f32 v27, v128, v129
	v_mov_b32_e32 v112, v62
	v_mov_b32_e32 v113, v63
	v_mfma_f32_16x16x32_bf16 v[20:23], v[108:111], v[24:27], v[20:23]
	ds_read2st64_b64 v[62:65], v29 offset0:8 offset1:12
	ds_read2st64_b64 v[108:111], v28 offset0:8 offset1:12
	v_add_u32_e32 v28, v74, v31
	v_add_u32_e32 v55, v28, v75
	v_mfma_f32_16x16x32_bf16 v[58:61], v[112:115], v[24:27], v[58:61]
	s_waitcnt lgkmcnt(1)
	v_mov_b32_e32 v112, v62
	v_mov_b32_e32 v113, v63
	s_waitcnt lgkmcnt(0)
	v_mov_b32_e32 v114, v108
	v_mov_b32_e32 v115, v109
	v_mov_b32_e32 v108, v64
	v_mov_b32_e32 v109, v65
	v_add_u32_e32 v56, v28, v76
	v_mfma_f32_16x16x32_bf16 v[104:107], v[112:115], v[24:27], v[104:107]
	v_cvt_pk_bf16_f32 v62, v130, v131
	v_cvt_pk_bf16_f32 v63, v132, v133
	v_cvt_pk_bf16_f32 v64, v134, v135
	v_mfma_f32_16x16x32_bf16 v[16:19], v[108:111], v[24:27], v[16:19]
	ds_read2st64_b64 v[24:27], v55 offset1:4
	ds_read2st64_b64 v[108:111], v56 offset1:4
	v_cvt_pk_bf16_f32 v65, v136, v137
	s_waitcnt lgkmcnt(1)
	v_mov_b32_e32 v28, v24
	v_mov_b32_e32 v29, v25
	s_waitcnt lgkmcnt(0)
	v_mov_b32_e32 v30, v108
	v_mov_b32_e32 v31, v109
	v_mov_b32_e32 v108, v26
	v_mov_b32_e32 v109, v27
	v_mfma_f32_16x16x32_bf16 v[28:31], v[28:31], v[62:65], v[58:61]
	s_nop 0
	v_mfma_f32_16x16x32_bf16 v[24:27], v[108:111], v[62:65], v[20:23]
	s_nop 0
	ds_read2st64_b64 v[58:61], v55 offset0:8 offset1:12
	ds_read2st64_b64 v[108:111], v56 offset0:8 offset1:12
	s_waitcnt lgkmcnt(1)
	v_mov_b32_e32 v20, v58
	v_mov_b32_e32 v21, v59
	s_waitcnt lgkmcnt(0)
	v_mov_b32_e32 v22, v108
	v_mov_b32_e32 v23, v109
	v_mov_b32_e32 v108, v60
	v_mov_b32_e32 v109, v61
	v_mfma_f32_16x16x32_bf16 v[20:23], v[20:23], v[62:65], v[104:107]
	s_nop 0
	v_mfma_f32_16x16x32_bf16 v[16:19], v[108:111], v[62:65], v[16:19]
	s_and_saveexec_b64 s[0:1], s[42:43]
	s_cbranch_execz .LBB0_403
	ds_write2st64_b32 v103, v38, v54 offset1:1
	ds_write2st64_b32 v103, v28, v29 offset0:2 offset1:3
	ds_write2st64_b32 v103, v30, v31 offset0:4 offset1:5
	ds_write2st64_b32 v103, v24, v25 offset0:6 offset1:7
	ds_write2st64_b32 v103, v26, v27 offset0:8 offset1:9
	ds_write2st64_b32 v103, v20, v21 offset0:10 offset1:11
	ds_write2st64_b32 v103, v22, v23 offset0:12 offset1:13
	ds_write2st64_b32 v103, v16, v17 offset0:14 offset1:15
	ds_write2st64_b32 v103, v18, v19 offset0:16 offset1:17
